# mixer queue order: the first 128 stick-breaking items are popped before the 128 longest FoX items (no waves idle-polling for the gate cumsums at phase start)
# speedup vs baseline: 1.0086x; 1.0072x over previous
; __global__ void __launch_bounds__(512, 2) mega_fwd(Args a) {
;     ...
;                 int it = 0; if (lane == 0) it = (int)atomicAdd(ctr, 1u); it = __builtin_amdgcn_readfirstlane(it) * 8 + sq;
;                 if (it >= 874) break;
;                 if (it < 138) {
;                     if (it >= 48) { __builtin_amdgcn_s_setprio(3); mlstm_item<false>(ub, yb, mscr, prm + 512, prm + 8, prm + 16, prm + 64, L + wave * ML_WSTRIDE, xcd + 8 * ((it - 48) / 15), (it - 48) % 15, lane); __builtin_amdgcn_s_setprio(0); }
;                     else fox_cumsum_item(ub, prm, fcl, ftot, (xcd + 8 * (it >> 3)) * 8 + (it & 7), lane);
;                     asm volatile("s_waitcnt vmcnt(0)" ::: "memory");
;                     if (lane == 0) atomicAdd(done + (it >= 48 ? 8 : 0), 1u);
;                 } else {
;                     const bool issb = (it >= 266 && it < 522), isc = (it >= 522 && it < 618), isfox = !isc && !issb;
;                     if (isfox && !((okmask >> xcd) & 1u)) { unsigned sp = 0u;
;                         while (__hip_atomic_load(done, __ATOMIC_RELAXED, __HIP_MEMORY_SCOPE_AGENT) < 48u) { __builtin_amdgcn_s_sleep(120); if (++sp > (1u << 17)) break; }
;                         __builtin_amdgcn_fence(__ATOMIC_ACQUIRE, "agent"); okmask |= 1u << xcd; }
;                     if (isc && !((okmask >> (8 + xcd)) & 1u)) { unsigned sp = 0u;
;                         while (__hip_atomic_load(done + 8, __ATOMIC_RELAXED, __HIP_MEMORY_SCOPE_AGENT) < 90u) { __builtin_amdgcn_s_sleep(120); if (++sp > (1u << 17)) break; }
;                         __builtin_amdgcn_fence(__ATOMIC_ACQUIRE, "agent"); okmask |= 1u << (8 + xcd); }
;                     if (isc) { const int ci = it - 522; __builtin_amdgcn_s_setprio(2); mlstm_item<true>(ub, yb, mscr, prm + 512, prm + 8, prm + 16, prm + 64, L + wave * ML_WSTRIDE, xcd + 8 * (ci >> 4), 15 - (ci & 15), lane); __builtin_amdgcn_s_setprio(0); }
;                     else { int aitem; if (issb) { const int ai = it - 266; aitem = (ai >> 2) * 80 + 48 + xcd + 8 * (ai & 3); } else { const int ai = (it < 266) ? it - 138 : it - 490; aitem = (ai / 6) * 80 + xcd + 8 * (ai % 6); }
;                         attn_mfma_item(ub, yb, fcl, ftot, L + wave * ML_WSTRIDE, aitem, lane); }
.LBB0_711:
	s_or_b64 exec, exec, s[0:1]
	v_readfirstlane_b32 s2, v1
	s_lshl_b32 s0, s2, 3
	v_readlane_b32 s1, v255, 13
	s_or_b32 s98, s0, s1
	s_cmpk_gt_i32 s98, 0x369
	s_cselect_b64 s[0:1], -1, 0
	s_and_b64 vcc, exec, s[0:1]
	s_cbranch_vccnz .LBB0_706
	s_cmpk_lt_i32 s98, 0x8a
	s_cbranch_scc1 .Lq_noremap
	s_cmpk_gt_i32 s98, 0x189
	s_cbranch_scc1 .Lq_noremap
	s_movk_i32 s3, 0x80
	s_cmpk_lt_i32 s98, 0x10a
	s_cselect_b32 s3, s3, 0xffffff80
	s_add_i32 s98, s98, s3
.Lq_noremap:
	v_writelane_b32 v255, s0, 14
	s_cmpk_gt_i32 s98, 0x89
	s_nop 0
	v_writelane_b32 v255, s1, 15
	s_mov_b64 s[0:1], -1
	s_cbranch_scc0 .LBB0_796
	v_writelane_b32 v255, s2, 16
	s_add_i32 s3, s98, 0xfffffd96
	s_cmp_lt_u32 s3, 0xfffffea0
	v_readlane_b32 s2, v255, 0
	s_cselect_b64 s[0:1], -1, 0
	s_and_b32 s2, s57, s2
	s_cmp_eq_u32 s2, 0
	s_cselect_b64 s[50:51], -1, 0
	s_and_b64 s[0:1], s[0:1], s[50:51]
	s_andn2_b64 vcc, exec, s[0:1]
	s_mov_b32 s48, s57
	s_cbranch_vccnz .LBB0_721
	s_mov_b32 s2, 0x20001
	s_branch .LBB0_716
